# in-proj A: workgroups with 8 tiles start in four groups a few microseconds apart (their slack) so that tile epilogue store bursts do not coincide
# speedup vs baseline: 1.0042x; 1.0042x over previous
.LBB0_164:
	s_and_b64 vcc, exec, s[42:43]
	s_cbranch_vccz .LBB0_191
	s_cmp_eq_u32 s57, 1
	s_cselect_b64 s[6:7], -1, 0
	s_and_b64 s[0:1], s[6:7], exec
	s_cselect_b32 s0, 33, 24
	s_lshl_b32 s90, s0, 6
	v_mov_b32_e32 v0, v216
	v_readlane_b32 s2, v253, 15
	s_cmp_ge_i32 s2, s90
	v_readfirstlane_b32 s11, v0
	v_readlane_b32 s3, v253, 16
	v_readlane_b32 s1, v254, 26
	s_cbranch_scc1 .LBB0_190
	s_cmp_lg_u32 s57, 1
	s_cbranch_scc1 .Ldither_done
	s_cmp_lt_u32 s2, 64
	s_cbranch_scc1 .Ldither_done
	s_bfe_u32 s32, s2, 0x20003
	s_cmp_eq_u32 s32, 0
	s_cbranch_scc1 .Ldither_done
.Ldither_loop:
	s_sleep 127
	s_sleep 64
	s_sub_u32 s32, s32, 1
	s_cmp_lg_u32 s32, 0
	s_cbranch_scc1 .Ldither_loop
.Ldither_done:
	s_waitcnt lgkmcnt(0)
	v_lshlrev_b32_e32 v2, 4, v0
	v_add_u32_e32 v3, 0x2000, v2
	v_ashrrev_i32_e32 v4, 31, v3
	v_lshrrev_b32_e32 v4, 22, v4
	v_add_u32_e32 v4, v3, v4
	v_ashrrev_i32_e32 v10, 10, v4
	v_mul_i32_i24_e32 v4, 0x400, v10
	v_sub_u32_e32 v3, v3, v4
	v_lshrrev_b32_e32 v4, 4, v3
	v_bitop3_b32 v3, v4, v3, 32 bitop3:0x6c
	v_ashrrev_i32_e32 v4, 31, v3
	v_lshrrev_b32_e32 v4, 26, v4
	v_add_u32_e32 v4, v3, v4
	v_lshlrev_b32_e32 v5, 3, v10
	s_and_b64 s[2:3], s[6:7], exec
	v_ashrrev_i32_e32 v11, 6, v4
	v_and_b32_e32 v5, -16, v5
	s_cselect_b32 s1, 0, 0x1080000
	v_readlane_b32 s2, v249, 6
	v_add_u32_e32 v5, v11, v5
	s_add_u32 s26, s2, s1
	v_and_b32_e32 v6, 3, v11
	s_mov_b32 s1, 0x1fffe0
	v_lshrrev_b32_e32 v7, 2, v5
	v_lshlrev_b32_e32 v8, 1, v5
	v_and_b32_e32 v4, 0xc0, v4
	v_and_or_b32 v6, v5, s1, v6
	v_and_b32_e32 v7, 4, v7
	v_and_b32_e32 v8, 24, v8
	v_sub_u32_e32 v3, v3, v4
	v_or3_b32 v6, v6, v7, v8
	v_lshlrev_b32_e32 v7, 5, v10
	v_ashrrev_i16_sdwa v3, v222, sext(v3) dst_sel:DWORD dst_unused:UNUSED_PAD src0_sel:DWORD src1_sel:BYTE_0
	v_and_b32_e32 v7, 32, v7
	v_bfe_i32 v12, v3, 0, 16
	v_add_lshl_u32 v3, v7, v12, 1
	v_lshl_add_u32 v150, v6, 11, v3
	v_lshl_add_u32 v152, v5, 11, v3
	v_bfe_i32 v3, v0, 27, 1
	v_lshrrev_b32_e32 v3, 22, v3
	v_add_u32_e32 v3, v2, v3
	v_and_b32_e32 v3, 0xfffffc00, v3
	v_sub_u32_e32 v2, v2, v3
	v_lshrrev_b32_e32 v3, 4, v2
	v_bitop3_b32 v3, v3, v2, 32 bitop3:0x6c
	v_ashrrev_i32_e32 v2, 31, v2
	v_lshrrev_b32_e32 v2, 26, v2
	v_add_u32_e32 v2, v3, v2
	v_ashrrev_i32_e32 v13, 6, v2
	v_ashrrev_i32_e32 v2, 31, v0
	v_lshrrev_b32_e32 v2, 26, v2
	v_add_u32_e32 v2, v0, v2
	v_ashrrev_i32_e32 v14, 6, v2
	v_lshlrev_b32_e32 v2, 3, v14
	v_and_b32_e32 v2, -16, v2
	v_add_u32_e32 v2, v13, v2
	v_and_b32_e32 v4, 3, v13
	v_lshrrev_b32_e32 v5, 2, v2
	v_lshlrev_b32_e32 v6, 1, v2
	v_and_or_b32 v4, v2, s1, v4
	v_and_b32_e32 v5, 4, v5
	v_and_b32_e32 v6, 24, v6
	v_or3_b32 v4, v4, v5, v6
	v_mul_i32_i24_e32 v6, 64, v13
	v_readlane_b32 s3, v249, 7
	v_sub_u32_e32 v3, v3, v6
	s_addc_u32 s27, s3, 0
	v_ashrrev_i16_sdwa v3, v222, sext(v3) dst_sel:DWORD dst_unused:UNUSED_PAD src0_sel:DWORD src1_sel:BYTE_0
	s_lshl_b32 s29, s0, 3
	v_bfe_i32 v15, v3, 0, 16
	v_cvt_f32_u32_e32 v3, s29
	v_lshlrev_b32_e32 v5, 5, v14
	v_and_b32_e32 v5, 32, v5
	v_add_lshl_u32 v5, v5, v15, 1
	s_waitcnt vmcnt(0)
	v_lshl_add_u32 v156, v2, 11, v5
	v_rcp_iflag_f32_e32 v2, v3
	v_readlane_b32 s0, v252, 40
	s_or_b32 s0, s29, s0
	v_readlane_b32 s1, v252, 39
	v_mul_f32_e32 v2, 0x4f7ffffe, v2
	v_cvt_u32_f32_e32 v2, v2
	s_sub_i32 s3, 0, s29
	s_mul_i32 s0, s0, s1
	v_readlane_b32 s1, v252, 31
	v_readfirstlane_b32 s30, v2
	s_mul_i32 s3, s3, s30
	s_add_i32 s0, s0, s1
	s_mul_hi_u32 s3, s30, s3
	s_abs_i32 s2, s0
	s_add_i32 s30, s30, s3
	s_mul_hi_u32 s3, s2, s30
	s_mul_i32 s4, s3, s29
	s_ashr_i32 s13, s11, 6
	s_sub_i32 s2, s2, s4
	s_ashr_i32 s12, s11, 8
	s_lshl_b32 s28, s13, 10
	s_ashr_i32 s1, s0, 31
	s_add_i32 s4, s3, 1
	s_sub_i32 s5, s2, s29
	s_cmp_ge_u32 s2, s29
	s_cselect_b32 s3, s4, s3
	s_cselect_b32 s2, s5, s2
	s_add_i32 s4, s3, 1
	s_cmp_ge_u32 s2, s29
	s_cselect_b32 s2, s4, s3
	s_xor_b32 s2, s2, s1
	s_sub_i32 s1, s2, s1
	s_lshl_b32 s2, s1, 3
	s_sub_i32 s3, 64, s2
	s_min_i32 s3, s3, 8
	s_sext_i32_i16 s4, s3
	v_cvt_f32_i32_e32 v2, s4
	s_mul_i32 s1, s1, s29
	s_sub_i32 s5, s0, s1
	s_sext_i32_i16 s0, s5
	v_lshl_add_u32 v154, v4, 11, v5
	v_cvt_f32_i32_e32 v3, s0
	v_rcp_iflag_f32_e32 v4, v2
	s_xor_b32 s0, s0, s4
	s_ashr_i32 s0, s0, 30
	s_or_b32 s4, s0, 1
	v_mul_f32_e32 v4, v3, v4
	v_trunc_f32_e32 v4, v4
	v_fma_f32 v3, -v4, v2, v3
	v_cvt_i32_f32_e32 v4, v4
	v_cmp_ge_f32_e64 s[0:1], |v3|, |v2|
	s_and_b64 s[0:1], s[0:1], exec
	s_cselect_b32 s0, s4, 0
	v_readfirstlane_b32 s1, v4
	s_add_i32 s10, s1, s0
	s_mul_i32 s0, s10, s3
	s_sub_i32 s0, s5, s0
	s_sext_i32_i16 s0, s0
	s_add_i32 s2, s2, s0
	s_ashr_i32 s3, s2, 31
	s_bfe_i64 s[4:5], s[10:11], 0x100000
	s_lshl_b64 s[0:1], s[2:3], 19
	s_lshl_b64 s[4:5], s[4:5], 19
	s_add_u32 s22, s26, s4
	s_addc_u32 s23, s27, s5
	s_add_i32 s31, s28, 0
	s_add_i32 m0, s31, 0x10000
	v_mov_b32_e32 v155, v1
	global_load_lds_dwordx4 v154, s[22:23]
	s_add_i32 m0, s31, 0x12000
	s_add_u32 s4, s22, 0x40000
	global_load_lds_dwordx4 v150, s[22:23]
	s_addc_u32 s5, s23, 0
	s_add_i32 m0, s31, 0x14000
	v_mov_b32_e32 v151, v1
	global_load_lds_dwordx4 v154, s[4:5]
	s_add_i32 m0, s31, 0x16000
	v_mov_b32_e32 v157, v1
	global_load_lds_dwordx4 v150, s[4:5]
	v_readlane_b32 s4, v252, 21
	v_readlane_b32 s5, v252, 22
	s_add_u32 s4, s4, s0
	s_addc_u32 s5, s5, s1
	s_add_i32 s34, s31, 0x2000
	s_mov_b32 m0, s31
	s_add_u32 s0, s4, 0x40000
	global_load_lds_dwordx4 v156, s[4:5]
	s_mov_b32 m0, s34
	s_addc_u32 s1, s5, 0
	s_add_i32 s35, s31, 0x4000
	global_load_lds_dwordx4 v152, s[4:5]
	s_mov_b32 m0, s35
	s_add_i32 s36, s31, 0x6000
	global_load_lds_dwordx4 v156, s[0:1]
	s_mov_b32 m0, s36
	v_mov_b32_e32 v153, v1
	global_load_lds_dwordx4 v152, s[0:1]
	s_cmp_eq_u32 s12, 1
	v_lshl_add_u64 v[8:9], s[22:23], 0, v[154:155]
	v_lshl_add_u64 v[6:7], s[22:23], 0, v[150:151]
	v_lshl_add_u64 v[2:3], s[4:5], 0, v[156:157]
	s_cselect_b64 s[0:1], -1, 0
	s_cmp_lg_u32 s12, 1
	v_lshl_add_u64 v[4:5], s[4:5], 0, v[152:153]
	s_cbranch_scc1 .LBB0_168
	s_barrier
